# P9 seam fix-up: per-seam counted waits (each seam's repair starts when its own boundary rows have landed)
# baseline (speedup 1.0000x reference)
.LBB0_1421:
	s_mov_b64 s[6:7], exec
	v_cmp_gt_u32_e32 vcc, 0x160, v215
	s_and_b64 exec, exec, vcc
	s_cbranch_execz .Lfx_done
	s_mul_i32 s8, s1, 0x580
	v_lshl_add_u32 v0, v215, 2, s8
	v_lshlrev_b32_e32 v9, 1, v0
	v_add_u32_e32 v10, 0x1600, v9
	s_add_u32 s28, s74, 0xc000000
	s_addc_u32 s29, s75, 0
	s_cmp_eq_u32 s30, 0
	s_cbranch_scc1 .Lfx_c0
	s_waitcnt vmcnt(24)
	s_lshl_b32 s18, s45, 8
	s_add_i32 s18, s18, -1
	s_mul_i32 s19, s18, 0x1600
	s_add_u32 s22, s28, s19
	s_addc_u32 s23, s29, 0
	v_pk_fma_f32 v[208:209], v[56:57], v[16:17], v[40:41]
	v_pk_fma_f32 v[210:211], v[58:59], v[18:19], v[42:43]
	v_pk_fma_f32 v[208:209], v[64:65], v[24:25], v[208:209]
	v_pk_fma_f32 v[210:211], v[66:67], v[26:27], v[210:211]
	v_pk_fma_f32 v[208:209], v[72:73], v[32:33], v[208:209]
	v_pk_fma_f32 v[210:211], v[74:75], v[34:35], v[210:211]
	v_pk_fma_f32 v[12:13], v[60:61], v[20:21], v[44:45]
	v_pk_fma_f32 v[14:15], v[62:63], v[22:23], v[46:47]
	v_pk_fma_f32 v[12:13], v[68:69], v[28:29], v[12:13]
	v_pk_fma_f32 v[14:15], v[70:71], v[30:31], v[14:15]
	v_pk_fma_f32 v[12:13], v[76:77], v[36:37], v[12:13]
	v_pk_fma_f32 v[14:15], v[78:79], v[38:39], v[14:15]
	v_pk_mul_f32 v[216:217], v[208:209], v[222:223]
	v_pk_mul_f32 v[218:219], v[210:211], v[222:223]
	v_exp_f32_e32 v216, v216
	v_exp_f32_e32 v217, v217
	v_exp_f32_e32 v218, v218
	v_exp_f32_e32 v219, v219
	v_pk_add_f32 v[216:217], v[216:217], 1.0 op_sel_hi:[1,0]
	v_pk_add_f32 v[218:219], v[218:219], 1.0 op_sel_hi:[1,0]
	v_rcp_f32_e32 v216, v216
	v_rcp_f32_e32 v217, v217
	v_rcp_f32_e32 v218, v218
	v_rcp_f32_e32 v219, v219
	v_pk_mul_f32 v[208:209], v[208:209], v[216:217]
	v_pk_mul_f32 v[210:211], v[210:211], v[218:219]
	v_pk_mul_f32 v[208:209], v[208:209], v[12:13]
	v_pk_mul_f32 v[210:211], v[210:211], v[14:15]
	v_cvt_pk_bf16_f32 v226, v208, v209
	v_cvt_pk_bf16_f32 v227, v210, v211
	global_store_dwordx2 v10, v[226:227], s[22:23]
.Lfx_c0:
	s_cmp_eq_u32 s31, 0
	s_cbranch_scc1 .Lfx_c1
	s_waitcnt vmcnt(16)
	s_lshl_b32 s18, s45, 8
	s_add_i32 s18, s18, 63
	s_mul_i32 s19, s18, 0x1600
	s_add_u32 s22, s28, s19
	s_addc_u32 s23, s29, 0
	v_pk_fma_f32 v[208:209], v[80:81], v[16:17], v[40:41]
	v_pk_fma_f32 v[210:211], v[82:83], v[18:19], v[42:43]
	v_pk_fma_f32 v[208:209], v[88:89], v[24:25], v[208:209]
	v_pk_fma_f32 v[210:211], v[90:91], v[26:27], v[210:211]
	v_pk_fma_f32 v[208:209], v[96:97], v[32:33], v[208:209]
	v_pk_fma_f32 v[210:211], v[98:99], v[34:35], v[210:211]
	v_pk_fma_f32 v[12:13], v[84:85], v[20:21], v[44:45]
	v_pk_fma_f32 v[14:15], v[86:87], v[22:23], v[46:47]
	v_pk_fma_f32 v[12:13], v[92:93], v[28:29], v[12:13]
	v_pk_fma_f32 v[14:15], v[94:95], v[30:31], v[14:15]
	v_pk_fma_f32 v[12:13], v[100:101], v[36:37], v[12:13]
	v_pk_fma_f32 v[14:15], v[102:103], v[38:39], v[14:15]
	v_pk_mul_f32 v[216:217], v[208:209], v[222:223]
	v_pk_mul_f32 v[218:219], v[210:211], v[222:223]
	v_exp_f32_e32 v216, v216
	v_exp_f32_e32 v217, v217
	v_exp_f32_e32 v218, v218
	v_exp_f32_e32 v219, v219
	v_pk_add_f32 v[216:217], v[216:217], 1.0 op_sel_hi:[1,0]
	v_pk_add_f32 v[218:219], v[218:219], 1.0 op_sel_hi:[1,0]
	v_rcp_f32_e32 v216, v216
	v_rcp_f32_e32 v217, v217
	v_rcp_f32_e32 v218, v218
	v_rcp_f32_e32 v219, v219
	v_pk_mul_f32 v[208:209], v[208:209], v[216:217]
	v_pk_mul_f32 v[210:211], v[210:211], v[218:219]
	v_pk_mul_f32 v[208:209], v[208:209], v[12:13]
	v_pk_mul_f32 v[210:211], v[210:211], v[14:15]
	v_cvt_pk_bf16_f32 v224, v208, v209
	v_cvt_pk_bf16_f32 v225, v210, v211
	global_store_dwordx2 v9, v[224:225], s[22:23]
	v_pk_fma_f32 v[208:209], v[88:89], v[16:17], v[40:41]
	v_pk_fma_f32 v[210:211], v[90:91], v[18:19], v[42:43]
	v_pk_fma_f32 v[208:209], v[96:97], v[24:25], v[208:209]
	v_pk_fma_f32 v[210:211], v[98:99], v[26:27], v[210:211]
	v_pk_fma_f32 v[208:209], v[104:105], v[32:33], v[208:209]
	v_pk_fma_f32 v[210:211], v[106:107], v[34:35], v[210:211]
	v_pk_fma_f32 v[12:13], v[92:93], v[20:21], v[44:45]
	v_pk_fma_f32 v[14:15], v[94:95], v[22:23], v[46:47]
	v_pk_fma_f32 v[12:13], v[100:101], v[28:29], v[12:13]
	v_pk_fma_f32 v[14:15], v[102:103], v[30:31], v[14:15]
	v_pk_fma_f32 v[12:13], v[108:109], v[36:37], v[12:13]
	v_pk_fma_f32 v[14:15], v[110:111], v[38:39], v[14:15]
	v_pk_mul_f32 v[216:217], v[208:209], v[222:223]
	v_pk_mul_f32 v[218:219], v[210:211], v[222:223]
	v_exp_f32_e32 v216, v216
	v_exp_f32_e32 v217, v217
	v_exp_f32_e32 v218, v218
	v_exp_f32_e32 v219, v219
	v_pk_add_f32 v[216:217], v[216:217], 1.0 op_sel_hi:[1,0]
	v_pk_add_f32 v[218:219], v[218:219], 1.0 op_sel_hi:[1,0]
	v_rcp_f32_e32 v216, v216
	v_rcp_f32_e32 v217, v217
	v_rcp_f32_e32 v218, v218
	v_rcp_f32_e32 v219, v219
	v_pk_mul_f32 v[208:209], v[208:209], v[216:217]
	v_pk_mul_f32 v[210:211], v[210:211], v[218:219]
	v_pk_mul_f32 v[208:209], v[208:209], v[12:13]
	v_pk_mul_f32 v[210:211], v[210:211], v[14:15]
	v_cvt_pk_bf16_f32 v226, v208, v209
	v_cvt_pk_bf16_f32 v227, v210, v211
	global_store_dwordx2 v10, v[226:227], s[22:23]
.Lfx_c1:
	s_cmp_eq_u32 s32, 0
	s_cbranch_scc1 .Lfx_c2
	s_waitcnt vmcnt(8)
	s_lshl_b32 s18, s45, 8
	s_add_i32 s18, s18, 127
	s_mul_i32 s19, s18, 0x1600
	s_add_u32 s22, s28, s19
	s_addc_u32 s23, s29, 0
	v_pk_fma_f32 v[208:209], v[112:113], v[16:17], v[40:41]
	v_pk_fma_f32 v[210:211], v[114:115], v[18:19], v[42:43]
	v_pk_fma_f32 v[208:209], v[120:121], v[24:25], v[208:209]
	v_pk_fma_f32 v[210:211], v[122:123], v[26:27], v[210:211]
	v_pk_fma_f32 v[208:209], v[128:129], v[32:33], v[208:209]
	v_pk_fma_f32 v[210:211], v[130:131], v[34:35], v[210:211]
	v_pk_fma_f32 v[12:13], v[116:117], v[20:21], v[44:45]
	v_pk_fma_f32 v[14:15], v[118:119], v[22:23], v[46:47]
	v_pk_fma_f32 v[12:13], v[124:125], v[28:29], v[12:13]
	v_pk_fma_f32 v[14:15], v[126:127], v[30:31], v[14:15]
	v_pk_fma_f32 v[12:13], v[132:133], v[36:37], v[12:13]
	v_pk_fma_f32 v[14:15], v[134:135], v[38:39], v[14:15]
	v_pk_mul_f32 v[216:217], v[208:209], v[222:223]
	v_pk_mul_f32 v[218:219], v[210:211], v[222:223]
	v_exp_f32_e32 v216, v216
	v_exp_f32_e32 v217, v217
	v_exp_f32_e32 v218, v218
	v_exp_f32_e32 v219, v219
	v_pk_add_f32 v[216:217], v[216:217], 1.0 op_sel_hi:[1,0]
	v_pk_add_f32 v[218:219], v[218:219], 1.0 op_sel_hi:[1,0]
	v_rcp_f32_e32 v216, v216
	v_rcp_f32_e32 v217, v217
	v_rcp_f32_e32 v218, v218
	v_rcp_f32_e32 v219, v219
	v_pk_mul_f32 v[208:209], v[208:209], v[216:217]
	v_pk_mul_f32 v[210:211], v[210:211], v[218:219]
	v_pk_mul_f32 v[208:209], v[208:209], v[12:13]
	v_pk_mul_f32 v[210:211], v[210:211], v[14:15]
	v_cvt_pk_bf16_f32 v224, v208, v209
	v_cvt_pk_bf16_f32 v225, v210, v211
	global_store_dwordx2 v9, v[224:225], s[22:23]
	v_pk_fma_f32 v[208:209], v[120:121], v[16:17], v[40:41]
	v_pk_fma_f32 v[210:211], v[122:123], v[18:19], v[42:43]
	v_pk_fma_f32 v[208:209], v[128:129], v[24:25], v[208:209]
	v_pk_fma_f32 v[210:211], v[130:131], v[26:27], v[210:211]
	v_pk_fma_f32 v[208:209], v[136:137], v[32:33], v[208:209]
	v_pk_fma_f32 v[210:211], v[138:139], v[34:35], v[210:211]
	v_pk_fma_f32 v[12:13], v[124:125], v[20:21], v[44:45]
	v_pk_fma_f32 v[14:15], v[126:127], v[22:23], v[46:47]
	v_pk_fma_f32 v[12:13], v[132:133], v[28:29], v[12:13]
	v_pk_fma_f32 v[14:15], v[134:135], v[30:31], v[14:15]
	v_pk_fma_f32 v[12:13], v[140:141], v[36:37], v[12:13]
	v_pk_fma_f32 v[14:15], v[142:143], v[38:39], v[14:15]
	v_pk_mul_f32 v[216:217], v[208:209], v[222:223]
	v_pk_mul_f32 v[218:219], v[210:211], v[222:223]
	v_exp_f32_e32 v216, v216
	v_exp_f32_e32 v217, v217
	v_exp_f32_e32 v218, v218
	v_exp_f32_e32 v219, v219
	v_pk_add_f32 v[216:217], v[216:217], 1.0 op_sel_hi:[1,0]
	v_pk_add_f32 v[218:219], v[218:219], 1.0 op_sel_hi:[1,0]
	v_rcp_f32_e32 v216, v216
	v_rcp_f32_e32 v217, v217
	v_rcp_f32_e32 v218, v218
	v_rcp_f32_e32 v219, v219
	v_pk_mul_f32 v[208:209], v[208:209], v[216:217]
	v_pk_mul_f32 v[210:211], v[210:211], v[218:219]
	v_pk_mul_f32 v[208:209], v[208:209], v[12:13]
	v_pk_mul_f32 v[210:211], v[210:211], v[14:15]
	v_cvt_pk_bf16_f32 v226, v208, v209
	v_cvt_pk_bf16_f32 v227, v210, v211
	global_store_dwordx2 v10, v[226:227], s[22:23]
.Lfx_c2:
	s_cmp_eq_u32 s33, 0
	s_cbranch_scc1 .Lfx_c3
	s_waitcnt vmcnt(0)
	s_lshl_b32 s18, s45, 8
	s_add_i32 s18, s18, 191
	s_mul_i32 s19, s18, 0x1600
	s_add_u32 s22, s28, s19
	s_addc_u32 s23, s29, 0
	v_pk_fma_f32 v[208:209], v[144:145], v[16:17], v[40:41]
	v_pk_fma_f32 v[210:211], v[146:147], v[18:19], v[42:43]
	v_pk_fma_f32 v[208:209], v[152:153], v[24:25], v[208:209]
	v_pk_fma_f32 v[210:211], v[154:155], v[26:27], v[210:211]
	v_pk_fma_f32 v[208:209], v[160:161], v[32:33], v[208:209]
	v_pk_fma_f32 v[210:211], v[162:163], v[34:35], v[210:211]
	v_pk_fma_f32 v[12:13], v[148:149], v[20:21], v[44:45]
	v_pk_fma_f32 v[14:15], v[150:151], v[22:23], v[46:47]
	v_pk_fma_f32 v[12:13], v[156:157], v[28:29], v[12:13]
	v_pk_fma_f32 v[14:15], v[158:159], v[30:31], v[14:15]
	v_pk_fma_f32 v[12:13], v[164:165], v[36:37], v[12:13]
	v_pk_fma_f32 v[14:15], v[166:167], v[38:39], v[14:15]
	v_pk_mul_f32 v[216:217], v[208:209], v[222:223]
	v_pk_mul_f32 v[218:219], v[210:211], v[222:223]
	v_exp_f32_e32 v216, v216
	v_exp_f32_e32 v217, v217
	v_exp_f32_e32 v218, v218
	v_exp_f32_e32 v219, v219
	v_pk_add_f32 v[216:217], v[216:217], 1.0 op_sel_hi:[1,0]
	v_pk_add_f32 v[218:219], v[218:219], 1.0 op_sel_hi:[1,0]
	v_rcp_f32_e32 v216, v216
	v_rcp_f32_e32 v217, v217
	v_rcp_f32_e32 v218, v218
	v_rcp_f32_e32 v219, v219
	v_pk_mul_f32 v[208:209], v[208:209], v[216:217]
	v_pk_mul_f32 v[210:211], v[210:211], v[218:219]
	v_pk_mul_f32 v[208:209], v[208:209], v[12:13]
	v_pk_mul_f32 v[210:211], v[210:211], v[14:15]
	v_cvt_pk_bf16_f32 v224, v208, v209
	v_cvt_pk_bf16_f32 v225, v210, v211
	global_store_dwordx2 v9, v[224:225], s[22:23]
	v_pk_fma_f32 v[208:209], v[152:153], v[16:17], v[40:41]
	v_pk_fma_f32 v[210:211], v[154:155], v[18:19], v[42:43]
	v_pk_fma_f32 v[208:209], v[160:161], v[24:25], v[208:209]
	v_pk_fma_f32 v[210:211], v[162:163], v[26:27], v[210:211]
	v_pk_fma_f32 v[208:209], v[168:169], v[32:33], v[208:209]
	v_pk_fma_f32 v[210:211], v[170:171], v[34:35], v[210:211]
	v_pk_fma_f32 v[12:13], v[156:157], v[20:21], v[44:45]
	v_pk_fma_f32 v[14:15], v[158:159], v[22:23], v[46:47]
	v_pk_fma_f32 v[12:13], v[164:165], v[28:29], v[12:13]
	v_pk_fma_f32 v[14:15], v[166:167], v[30:31], v[14:15]
	v_pk_fma_f32 v[12:13], v[172:173], v[36:37], v[12:13]
	v_pk_fma_f32 v[14:15], v[174:175], v[38:39], v[14:15]
	v_pk_mul_f32 v[216:217], v[208:209], v[222:223]
	v_pk_mul_f32 v[218:219], v[210:211], v[222:223]
	v_exp_f32_e32 v216, v216
	v_exp_f32_e32 v217, v217
	v_exp_f32_e32 v218, v218
	v_exp_f32_e32 v219, v219
	v_pk_add_f32 v[216:217], v[216:217], 1.0 op_sel_hi:[1,0]
	v_pk_add_f32 v[218:219], v[218:219], 1.0 op_sel_hi:[1,0]
	v_rcp_f32_e32 v216, v216
	v_rcp_f32_e32 v217, v217
	v_rcp_f32_e32 v218, v218
	v_rcp_f32_e32 v219, v219
	v_pk_mul_f32 v[208:209], v[208:209], v[216:217]
	v_pk_mul_f32 v[210:211], v[210:211], v[218:219]
	v_pk_mul_f32 v[208:209], v[208:209], v[12:13]
	v_pk_mul_f32 v[210:211], v[210:211], v[14:15]
	v_cvt_pk_bf16_f32 v226, v208, v209
	v_cvt_pk_bf16_f32 v227, v210, v211
	global_store_dwordx2 v10, v[226:227], s[22:23]
.Lfx_c3:
	s_cmp_eq_u32 s34, 0
	s_cbranch_scc1 .Lfx_c4
	s_waitcnt vmcnt(0)
	s_lshl_b32 s18, s45, 8
	s_add_i32 s18, s18, 255
	s_mul_i32 s19, s18, 0x1600
	s_add_u32 s22, s28, s19
	s_addc_u32 s23, s29, 0
	v_pk_fma_f32 v[208:209], v[176:177], v[16:17], v[40:41]
	v_pk_fma_f32 v[210:211], v[178:179], v[18:19], v[42:43]
	v_pk_fma_f32 v[208:209], v[184:185], v[24:25], v[208:209]
	v_pk_fma_f32 v[210:211], v[186:187], v[26:27], v[210:211]
	v_pk_fma_f32 v[208:209], v[192:193], v[32:33], v[208:209]
	v_pk_fma_f32 v[210:211], v[194:195], v[34:35], v[210:211]
	v_pk_fma_f32 v[12:13], v[180:181], v[20:21], v[44:45]
	v_pk_fma_f32 v[14:15], v[182:183], v[22:23], v[46:47]
	v_pk_fma_f32 v[12:13], v[188:189], v[28:29], v[12:13]
	v_pk_fma_f32 v[14:15], v[190:191], v[30:31], v[14:15]
	v_pk_fma_f32 v[12:13], v[196:197], v[36:37], v[12:13]
	v_pk_fma_f32 v[14:15], v[198:199], v[38:39], v[14:15]
	v_pk_mul_f32 v[216:217], v[208:209], v[222:223]
	v_pk_mul_f32 v[218:219], v[210:211], v[222:223]
	v_exp_f32_e32 v216, v216
	v_exp_f32_e32 v217, v217
	v_exp_f32_e32 v218, v218
	v_exp_f32_e32 v219, v219
	v_pk_add_f32 v[216:217], v[216:217], 1.0 op_sel_hi:[1,0]
	v_pk_add_f32 v[218:219], v[218:219], 1.0 op_sel_hi:[1,0]
	v_rcp_f32_e32 v216, v216
	v_rcp_f32_e32 v217, v217
	v_rcp_f32_e32 v218, v218
	v_rcp_f32_e32 v219, v219
	v_pk_mul_f32 v[208:209], v[208:209], v[216:217]
	v_pk_mul_f32 v[210:211], v[210:211], v[218:219]
	v_pk_mul_f32 v[208:209], v[208:209], v[12:13]
	v_pk_mul_f32 v[210:211], v[210:211], v[14:15]
	v_cvt_pk_bf16_f32 v224, v208, v209
	v_cvt_pk_bf16_f32 v225, v210, v211
	global_store_dwordx2 v9, v[224:225], s[22:23]
